# GLU epilogue: y rows and bias of a column half requested together (two waits per tile instead of sixteen)
# baseline (speedup 1.0000x reference)
; #define PG8_STAGE(bufoff, gbase, voff) do { _Pragma("unroll") for (int _i = 0; _i < 2; ++_i) \
;         __builtin_amdgcn_global_load_lds((const unsigned*)((const char*)(gbase) + (voff)[_i]), (LAS unsigned*)(lds + (bufoff) + ldsw + _i * 8192), 16, 0, 0); } while (0)
; #define PG8_LDA(dst, b, h) do { _Pragma("unroll") for (int m = 0; m < 4; ++m) _Pragma("unroll") for (int k = 0; k < 2; ++k) dst[m][k] = *(const LAS bf16x8*)(lds + PG8_SA(b, h) + aoff + m * 2048 + k * 1024); } while (0)
; #define PG8_LDB(dst, b, h) do { _Pragma("unroll") for (int n = 0; n < 2; ++n) _Pragma("unroll") for (int k = 0; k < 2; ++k) dst[n][k] = *(const LAS bf16x8*)(lds + PG8_SB(b, h) + boff + n * 2048 + k * 1024); } while (0)
; #define PG8_MMA(ai, bj, At, Bt) do { __builtin_amdgcn_s_setprio(1); _Pragma("unroll") for (int m = 0; m < 4; ++m) _Pragma("unroll") for (int n = 0; n < 2; ++n) _Pragma("unroll") for (int k = 0; k < 2; ++k) \
;         acc[ai][bj][m][n] = __builtin_amdgcn_mfma_f32_16x16x32_bf16(Bt[n][k], At[m][k], acc[ai][bj][m][n], 0, 0, 0); __builtin_amdgcn_s_setprio(0); } while (0)
; #define PG8_WAIT_V(n) asm volatile("s_waitcnt vmcnt(" #n ")" ::: "memory")
; #define PG8_WAIT_L(n) asm volatile("s_waitcnt lgkmcnt(" #n ")" ::: "memory")
; #define PG8_BAR __builtin_amdgcn_s_barrier()
; #define PG8_SCHED __builtin_amdgcn_sched_barrier(0)
; template <class Epi>
; __device__ __forceinline__ void gemm_phase(LAS unsigned char* lds, const Gemm g, const TileOrder& S, const Epi& E) {
;     ...
;             PG8_LDB(B0, 0, 0); PG8_SCHED; PG8_LDA(At, 0, 0); PG8_STAGE(PG8_SA(1, 1), a1 + hstepA, voffA);
;             PG8_WAIT_L(8); PG8_BAR; PG8_WAIT_L(0); PG8_MMA(0, 0, At, B0); PG8_BAR; PG8_SCHED;
;             PG8_LDB(B1, 0, 1); PG8_STAGE(PG8_SB(0, 0), b2, voffB);
;             PG8_BAR; PG8_WAIT_L(0); PG8_MMA(0, 1, At, B1); PG8_BAR;
;             PG8_LDA(At, 0, 1); PG8_STAGE(PG8_SA(0, 0), a2, voffA);
;             PG8_BAR; PG8_WAIT_L(0); PG8_MMA(1, 0, At, B0); PG8_BAR; PG8_SCHED;
;             PG8_STAGE(PG8_SB(0, 1), b2 + hstepB, voffB);
;             PG8_WAIT_V(6); PG8_BAR; PG8_MMA(1, 1, At, B1); PG8_BAR;
;             PG8_LDB(B0, 1, 0); PG8_SCHED; PG8_LDA(At, 1, 0); PG8_STAGE(PG8_SA(0, 1), a2 + hstepA, voffA);
;             PG8_WAIT_L(8); PG8_BAR; PG8_WAIT_L(0); PG8_MMA(0, 0, At, B0); PG8_BAR; PG8_SCHED;
.LBB0_759:
	v_add_u32_e32 v170, s64, v174
	ds_read_b128 v[122:125], v170
	ds_read_b128 v[126:129], v170 offset:1024
	ds_read_b128 v[166:169], v170 offset:2048
	ds_read_b128 v[170:173], v170 offset:3072
	s_add_u32 s20, s18, 0xfffc0080
	s_addc_u32 s21, s19, -1
	s_cmp_eq_u32 s48, 12
	s_cselect_b32 s23, s13, s21
	s_cselect_b32 s22, s44, s20
	s_cselect_b32 s21, s11, s47
	s_cselect_b32 s20, s45, s46
	v_lshl_add_u64 v[226:227], s[18:19], 0, v[162:163]
	s_add_i32 m0, s29, 0xc000
	ds_read_b128 v[194:197], v193
	ds_read_b128 v[198:201], v193 offset:1024
	ds_read_b128 v[202:205], v193 offset:2048
	ds_read_b128 v[206:209], v193 offset:3072
	ds_read_b128 v[210:213], v193 offset:4096
	ds_read_b128 v[214:217], v193 offset:5120
	ds_read_b128 v[218:221], v193 offset:6144
	ds_read_b128 v[222:225], v193 offset:7168
	global_load_lds_dwordx4 v[226:227], off
	v_lshl_add_u64 v[226:227], s[18:19], 0, v[164:165]
	s_add_i32 m0, s29, 0xe000
	s_nop 0
	global_load_lds_dwordx4 v[226:227], off
	s_waitcnt lgkmcnt(8)
	s_barrier
	s_waitcnt lgkmcnt(0)
	s_setprio 1
	s_waitcnt lgkmcnt(0)
	v_mfma_f32_16x16x32_bf16 v[134:137], v[122:125], v[194:197], v[134:137]
	v_mfma_f32_16x16x32_bf16 v[130:133], v[166:169], v[194:197], v[130:133]
	v_mfma_f32_16x16x32_bf16 v[118:121], v[122:125], v[202:205], v[118:121]
	v_mfma_f32_16x16x32_bf16 v[114:117], v[166:169], v[202:205], v[114:117]
	v_mfma_f32_16x16x32_bf16 v[110:113], v[122:125], v[210:213], v[110:113]
	v_mfma_f32_16x16x32_bf16 v[106:109], v[166:169], v[210:213], v[106:109]
	v_mfma_f32_16x16x32_bf16 v[102:105], v[122:125], v[218:221], v[102:105]
	v_mfma_f32_16x16x32_bf16 v[98:101], v[166:169], v[218:221], v[98:101]
	v_mfma_f32_16x16x32_bf16 v[134:137], v[126:129], v[198:201], v[134:137]
	v_mfma_f32_16x16x32_bf16 v[130:133], v[170:173], v[198:201], v[130:133]
	v_mfma_f32_16x16x32_bf16 v[118:121], v[126:129], v[206:209], v[118:121]
	v_mfma_f32_16x16x32_bf16 v[114:117], v[170:173], v[206:209], v[114:117]
	v_mfma_f32_16x16x32_bf16 v[110:113], v[126:129], v[214:217], v[110:113]
	v_mfma_f32_16x16x32_bf16 v[106:109], v[170:173], v[214:217], v[106:109]
	v_mfma_f32_16x16x32_bf16 v[102:105], v[126:129], v[222:225], v[102:105]
	v_mfma_f32_16x16x32_bf16 v[98:101], v[170:173], v[222:225], v[98:101]
	s_setprio 0
	s_barrier
	s_add_i32 s49, 0, 0x14000
	s_add_i32 s42, s64, s28
	v_add_u32_e32 v238, s49, v174
	v_lshl_add_u64 v[242:243], s[20:21], 0, v[0:1]
	s_mov_b32 m0, s42
	ds_read_b128 v[226:229], v238
	ds_read_b128 v[230:233], v238 offset:1024
	ds_read_b128 v[234:237], v238 offset:2048
	ds_read_b128 v[238:241], v238 offset:3072
	global_load_lds_dwordx4 v[242:243], off
	v_lshl_add_u64 v[244:245], s[20:21], 0, v[156:157]
	s_add_i32 m0, s42, 0x2000
	s_nop 0
	global_load_lds_dwordx4 v[244:245], off
	s_barrier
	s_waitcnt lgkmcnt(0)
	s_setprio 1
	s_waitcnt lgkmcnt(0)
	v_mfma_f32_16x16x32_bf16 v[70:73], v[226:229], v[194:197], v[70:73]
	v_mfma_f32_16x16x32_bf16 v[66:69], v[234:237], v[194:197], v[66:69]
	v_mfma_f32_16x16x32_bf16 v[62:65], v[226:229], v[202:205], v[62:65]
	v_mfma_f32_16x16x32_bf16 v[58:61], v[234:237], v[202:205], v[58:61]
	v_mfma_f32_16x16x32_bf16 v[54:57], v[226:229], v[210:213], v[54:57]
	v_mfma_f32_16x16x32_bf16 v[50:53], v[234:237], v[210:213], v[50:53]
	v_mfma_f32_16x16x32_bf16 v[38:41], v[226:229], v[218:221], v[38:41]
	v_mfma_f32_16x16x32_bf16 v[34:37], v[234:237], v[218:221], v[34:37]
	v_mfma_f32_16x16x32_bf16 v[70:73], v[230:233], v[198:201], v[70:73]
	v_mfma_f32_16x16x32_bf16 v[66:69], v[238:241], v[198:201], v[66:69]
	v_mfma_f32_16x16x32_bf16 v[62:65], v[230:233], v[206:209], v[62:65]
	v_mfma_f32_16x16x32_bf16 v[58:61], v[238:241], v[206:209], v[58:61]
	v_mfma_f32_16x16x32_bf16 v[54:57], v[230:233], v[214:217], v[54:57]
	v_mfma_f32_16x16x32_bf16 v[50:53], v[238:241], v[214:217], v[50:53]
	v_mfma_f32_16x16x32_bf16 v[38:41], v[230:233], v[222:225], v[38:41]
	v_mfma_f32_16x16x32_bf16 v[34:37], v[238:241], v[222:225], v[34:37]
	s_setprio 0
	s_mov_b32 m0, s29
	v_lshl_add_u64 v[246:247], s[22:23], 0, v[160:161]
	s_barrier
	ds_read_b128 v[194:197], v193 offset:16384
	ds_read_b128 v[198:201], v193 offset:17408
	ds_read_b128 v[202:205], v193 offset:18432
	ds_read_b128 v[206:209], v193 offset:19456
	ds_read_b128 v[210:213], v193 offset:20480
	ds_read_b128 v[214:217], v193 offset:21504
	ds_read_b128 v[218:221], v193 offset:22528
	ds_read_b128 v[222:225], v193 offset:23552
	global_load_lds_dwordx4 v[246:247], off
	v_lshl_add_u64 v[248:249], s[22:23], 0, v[158:159]
	s_mov_b32 m0, s30
	s_nop 0
	global_load_lds_dwordx4 v[248:249], off
	s_barrier
	s_waitcnt lgkmcnt(0)
	s_setprio 1
	s_waitcnt lgkmcnt(0)
	v_mfma_f32_16x16x32_bf16 v[94:97], v[122:125], v[194:197], v[94:97]
	v_mfma_f32_16x16x32_bf16 v[90:93], v[166:169], v[194:197], v[90:93]
	v_mfma_f32_16x16x32_bf16 v[86:89], v[122:125], v[202:205], v[86:89]
	v_mfma_f32_16x16x32_bf16 v[82:85], v[166:169], v[202:205], v[82:85]
	v_mfma_f32_16x16x32_bf16 v[78:81], v[122:125], v[210:213], v[78:81]
	v_mfma_f32_16x16x32_bf16 v[74:77], v[166:169], v[210:213], v[74:77]
	v_mfma_f32_16x16x32_bf16 v[46:49], v[122:125], v[218:221], v[46:49]
	v_mfma_f32_16x16x32_bf16 v[42:45], v[166:169], v[218:221], v[42:45]
	v_mfma_f32_16x16x32_bf16 v[94:97], v[126:129], v[198:201], v[94:97]
	v_mfma_f32_16x16x32_bf16 v[90:93], v[170:173], v[198:201], v[90:93]
	v_mfma_f32_16x16x32_bf16 v[86:89], v[126:129], v[206:209], v[86:89]
	v_mfma_f32_16x16x32_bf16 v[82:85], v[170:173], v[206:209], v[82:85]
	v_mfma_f32_16x16x32_bf16 v[78:81], v[126:129], v[214:217], v[78:81]
	v_mfma_f32_16x16x32_bf16 v[74:77], v[170:173], v[214:217], v[74:77]
	v_mfma_f32_16x16x32_bf16 v[46:49], v[126:129], v[222:225], v[46:49]
	v_mfma_f32_16x16x32_bf16 v[42:45], v[170:173], v[222:225], v[42:45]
	s_setprio 0
	s_barrier
; #define PG8_STAGE(bufoff, gbase, voff) do { _Pragma("unroll") for (int _i = 0; _i < 2; ++_i) \
;         __builtin_amdgcn_global_load_lds((const unsigned*)((const char*)(gbase) + (voff)[_i]), (LAS unsigned*)(lds + (bufoff) + ldsw + _i * 8192), 16, 0, 0); } while (0)
; #define PG8_LDA(dst, b, h) do { _Pragma("unroll") for (int m = 0; m < 4; ++m) _Pragma("unroll") for (int k = 0; k < 2; ++k) dst[m][k] = *(const LAS bf16x8*)(lds + PG8_SA(b, h) + aoff + m * 2048 + k * 1024); } while (0)
; #define PG8_LDB(dst, b, h) do { _Pragma("unroll") for (int n = 0; n < 2; ++n) _Pragma("unroll") for (int k = 0; k < 2; ++k) dst[n][k] = *(const LAS bf16x8*)(lds + PG8_SB(b, h) + boff + n * 2048 + k * 1024); } while (0)
; #define PG8_MMA(ai, bj, At, Bt) do { __builtin_amdgcn_s_setprio(1); _Pragma("unroll") for (int m = 0; m < 4; ++m) _Pragma("unroll") for (int n = 0; n < 2; ++n) _Pragma("unroll") for (int k = 0; k < 2; ++k) \
;         acc[ai][bj][m][n] = __builtin_amdgcn_mfma_f32_16x16x32_bf16(Bt[n][k], At[m][k], acc[ai][bj][m][n], 0, 0, 0); __builtin_amdgcn_s_setprio(0); } while (0)
; #define PG8_WAIT_V(n) asm volatile("s_waitcnt vmcnt(" #n ")" ::: "memory")
; #define PG8_WAIT_L(n) asm volatile("s_waitcnt lgkmcnt(" #n ")" ::: "memory")
; #define PG8_BAR __builtin_amdgcn_s_barrier()
; #define PG8_SCHED __builtin_amdgcn_sched_barrier(0)
; template <class Epi>
; __device__ __forceinline__ void gemm_phase(LAS unsigned char* lds, const Gemm g, const TileOrder& S, const Epi& E) {
;     ...
;             PG8_STAGE(PG8_SB(0, 1), b2 + hstepB, voffB);
;             PG8_WAIT_V(6); PG8_BAR; PG8_MMA(1, 1, At, B1); PG8_BAR;
;             PG8_LDB(B0, 1, 0); PG8_SCHED; PG8_LDA(At, 1, 0); PG8_STAGE(PG8_SA(0, 1), a2 + hstepA, voffA);
;             PG8_WAIT_L(8); PG8_BAR; PG8_WAIT_L(0); PG8_MMA(0, 0, At, B0); PG8_BAR; PG8_SCHED;
;             PG8_LDB(B1, 1, 1); PG8_STAGE(PG8_SB(1, 0), b3, voffB);
;             PG8_BAR; PG8_WAIT_L(0); PG8_MMA(0, 1, At, B1); PG8_BAR;
;             PG8_LDA(At, 1, 1); PG8_STAGE(PG8_SA(1, 0), a3, voffA);
;             PG8_BAR; PG8_WAIT_L(0); PG8_MMA(1, 0, At, B0); PG8_BAR; PG8_SCHED;
	s_add_u32 s42, s20, 0x40000
	s_addc_u32 s43, s21, 0
	s_add_i32 s49, s49, s28
	v_lshl_add_u64 v[122:123], s[42:43], 0, v[0:1]
	s_mov_b32 m0, s49
	s_nop 0
	global_load_lds_dwordx4 v[122:123], off
	v_lshl_add_u64 v[122:123], s[42:43], 0, v[156:157]
	s_add_i32 m0, s49, 0x2000
	s_nop 0
	global_load_lds_dwordx4 v[122:123], off
	s_waitcnt vmcnt(6)
	s_barrier
	s_setprio 1
	v_mfma_f32_16x16x32_bf16 v[30:33], v[226:229], v[194:197], v[30:33]
	v_mfma_f32_16x16x32_bf16 v[26:29], v[234:237], v[194:197], v[26:29]
	v_mfma_f32_16x16x32_bf16 v[22:25], v[226:229], v[202:205], v[22:25]
	v_mfma_f32_16x16x32_bf16 v[18:21], v[234:237], v[202:205], v[18:21]
	v_mfma_f32_16x16x32_bf16 v[14:17], v[226:229], v[210:213], v[14:17]
	v_mfma_f32_16x16x32_bf16 v[10:13], v[234:237], v[210:213], v[10:13]
	v_mfma_f32_16x16x32_bf16 v[6:9], v[226:229], v[218:221], v[6:9]
	v_mfma_f32_16x16x32_bf16 v[2:5], v[234:237], v[218:221], v[2:5]
	v_mfma_f32_16x16x32_bf16 v[30:33], v[230:233], v[198:201], v[30:33]
	v_mfma_f32_16x16x32_bf16 v[26:29], v[238:241], v[198:201], v[26:29]
	v_mfma_f32_16x16x32_bf16 v[22:25], v[230:233], v[206:209], v[22:25]
	v_mfma_f32_16x16x32_bf16 v[18:21], v[238:241], v[206:209], v[18:21]
	v_mfma_f32_16x16x32_bf16 v[14:17], v[230:233], v[214:217], v[14:17]
	v_mfma_f32_16x16x32_bf16 v[10:13], v[238:241], v[214:217], v[10:13]
	v_mfma_f32_16x16x32_bf16 v[6:9], v[230:233], v[222:225], v[6:9]
	v_mfma_f32_16x16x32_bf16 v[2:5], v[238:241], v[222:225], v[2:5]
	s_setprio 0
	s_add_i32 s42, 0, 0x18000
	v_add_u32_e32 v170, s42, v174
	s_barrier
	ds_read_b128 v[122:125], v170
	ds_read_b128 v[126:129], v170 offset:1024
	ds_read_b128 v[166:169], v170 offset:2048
	ds_read_b128 v[170:173], v170 offset:3072
	s_add_u32 s22, s22, 0x40000
	s_addc_u32 s23, s23, 0
	s_mov_b32 m0, s31
	v_lshl_add_u64 v[226:227], s[22:23], 0, v[160:161]
	ds_read_b128 v[194:197], v193 offset:32768
	ds_read_b128 v[198:201], v193 offset:33792
	ds_read_b128 v[202:205], v193 offset:34816
	ds_read_b128 v[206:209], v193 offset:35840
	ds_read_b128 v[210:213], v193 offset:36864
	ds_read_b128 v[214:217], v193 offset:37888
	ds_read_b128 v[218:221], v193 offset:38912
	ds_read_b128 v[222:225], v193 offset:39936
	global_load_lds_dwordx4 v[226:227], off
	v_lshl_add_u64 v[226:227], s[22:23], 0, v[158:159]
	s_mov_b32 m0, s34
	s_nop 0
	global_load_lds_dwordx4 v[226:227], off
	s_waitcnt lgkmcnt(8)
	s_barrier
	s_waitcnt lgkmcnt(0)
	s_setprio 1
	s_waitcnt lgkmcnt(0)
	v_mfma_f32_16x16x32_bf16 v[134:137], v[122:125], v[194:197], v[134:137]
	v_mfma_f32_16x16x32_bf16 v[130:133], v[166:169], v[194:197], v[130:133]
	v_mfma_f32_16x16x32_bf16 v[118:121], v[122:125], v[202:205], v[118:121]
	v_mfma_f32_16x16x32_bf16 v[114:117], v[166:169], v[202:205], v[114:117]
	v_mfma_f32_16x16x32_bf16 v[110:113], v[122:125], v[210:213], v[110:113]
	v_mfma_f32_16x16x32_bf16 v[106:109], v[166:169], v[210:213], v[106:109]
	v_mfma_f32_16x16x32_bf16 v[102:105], v[122:125], v[218:221], v[102:105]
	v_mfma_f32_16x16x32_bf16 v[98:101], v[166:169], v[218:221], v[98:101]
	v_mfma_f32_16x16x32_bf16 v[134:137], v[126:129], v[198:201], v[134:137]
	v_mfma_f32_16x16x32_bf16 v[130:133], v[170:173], v[198:201], v[130:133]
	v_mfma_f32_16x16x32_bf16 v[118:121], v[126:129], v[206:209], v[118:121]
	v_mfma_f32_16x16x32_bf16 v[114:117], v[170:173], v[206:209], v[114:117]
	v_mfma_f32_16x16x32_bf16 v[110:113], v[126:129], v[214:217], v[110:113]
	v_mfma_f32_16x16x32_bf16 v[106:109], v[170:173], v[214:217], v[106:109]
	v_mfma_f32_16x16x32_bf16 v[102:105], v[126:129], v[222:225], v[102:105]
	v_mfma_f32_16x16x32_bf16 v[98:101], v[170:173], v[222:225], v[98:101]
	s_setprio 0
	s_barrier
	s_add_i32 s22, 0, 0x1c000
	s_add_i32 s23, s42, s28
	v_add_u32_e32 v238, s22, v174
	v_lshl_add_u64 v[242:243], v[242:243], 0, s[58:59]
	s_mov_b32 m0, s23
	ds_read_b128 v[226:229], v238
	ds_read_b128 v[230:233], v238 offset:1024
	ds_read_b128 v[234:237], v238 offset:2048
	ds_read_b128 v[238:241], v238 offset:3072
	global_load_lds_dwordx4 v[242:243], off
	v_lshl_add_u64 v[242:243], v[244:245], 0, s[58:59]
	s_add_i32 m0, s23, 0x2000
	s_nop 0
	global_load_lds_dwordx4 v[242:243], off
	s_barrier
	s_waitcnt lgkmcnt(0)
	s_setprio 1
	s_waitcnt lgkmcnt(0)
	v_mfma_f32_16x16x32_bf16 v[70:73], v[226:229], v[194:197], v[70:73]
	v_mfma_f32_16x16x32_bf16 v[66:69], v[234:237], v[194:197], v[66:69]
	v_mfma_f32_16x16x32_bf16 v[62:65], v[226:229], v[202:205], v[62:65]
	v_mfma_f32_16x16x32_bf16 v[58:61], v[234:237], v[202:205], v[58:61]
	v_mfma_f32_16x16x32_bf16 v[54:57], v[226:229], v[210:213], v[54:57]
	v_mfma_f32_16x16x32_bf16 v[50:53], v[234:237], v[210:213], v[50:53]
	v_mfma_f32_16x16x32_bf16 v[38:41], v[226:229], v[218:221], v[38:41]
	v_mfma_f32_16x16x32_bf16 v[34:37], v[234:237], v[218:221], v[34:37]
	v_mfma_f32_16x16x32_bf16 v[70:73], v[230:233], v[198:201], v[70:73]
	v_mfma_f32_16x16x32_bf16 v[66:69], v[238:241], v[198:201], v[66:69]
	v_mfma_f32_16x16x32_bf16 v[62:65], v[230:233], v[206:209], v[62:65]
	v_mfma_f32_16x16x32_bf16 v[58:61], v[238:241], v[206:209], v[58:61]
	v_mfma_f32_16x16x32_bf16 v[54:57], v[230:233], v[214:217], v[54:57]
	v_mfma_f32_16x16x32_bf16 v[50:53], v[238:241], v[214:217], v[50:53]
	v_mfma_f32_16x16x32_bf16 v[38:41], v[230:233], v[222:225], v[38:41]
	v_mfma_f32_16x16x32_bf16 v[34:37], v[238:241], v[222:225], v[34:37]
	s_setprio 0
	s_mov_b32 m0, s35
	v_lshl_add_u64 v[242:243], v[246:247], 0, s[58:59]
	s_barrier
	ds_read_b128 v[194:197], v193 offset:49152
	ds_read_b128 v[198:201], v193 offset:50176
	ds_read_b128 v[202:205], v193 offset:51200
	ds_read_b128 v[206:209], v193 offset:52224
	ds_read_b128 v[210:213], v193 offset:53248
	ds_read_b128 v[214:217], v193 offset:54272
	ds_read_b128 v[218:221], v193 offset:55296
	ds_read_b128 v[222:225], v193 offset:56320
	global_load_lds_dwordx4 v[242:243], off
	v_lshl_add_u64 v[242:243], v[248:249], 0, s[58:59]
	s_mov_b32 m0, s36
	s_nop 0
	global_load_lds_dwordx4 v[242:243], off
	s_barrier
; #define PG8_STAGE(bufoff, gbase, voff) do { _Pragma("unroll") for (int _i = 0; _i < 2; ++_i) \
;         __builtin_amdgcn_global_load_lds((const unsigned*)((const char*)(gbase) + (voff)[_i]), (LAS unsigned*)(lds + (bufoff) + ldsw + _i * 8192), 16, 0, 0); } while (0)
; #define PG8_MMA(ai, bj, At, Bt) do { __builtin_amdgcn_s_setprio(1); _Pragma("unroll") for (int m = 0; m < 4; ++m) _Pragma("unroll") for (int n = 0; n < 2; ++n) _Pragma("unroll") for (int k = 0; k < 2; ++k) \
;         acc[ai][bj][m][n] = __builtin_amdgcn_mfma_f32_16x16x32_bf16(Bt[n][k], At[m][k], acc[ai][bj][m][n], 0, 0, 0); __builtin_amdgcn_s_setprio(0); } while (0)
; #define PG8_WAIT_V(n) asm volatile("s_waitcnt vmcnt(" #n ")" ::: "memory")
; #define PG8_WAIT_L(n) asm volatile("s_waitcnt lgkmcnt(" #n ")" ::: "memory")
; #define PG8_BAR __builtin_amdgcn_s_barrier()
; #define PG8_SCHED __builtin_amdgcn_sched_barrier(0)
; template <class Epi>
; __device__ __forceinline__ void gemm_phase(LAS unsigned char* lds, const Gemm g, const TileOrder& S, const Epi& E) {
;     ...
;             PG8_BAR; PG8_WAIT_L(0); PG8_MMA(1, 0, At, B0); PG8_BAR; PG8_SCHED;
;             PG8_STAGE(PG8_SB(1, 1), b3 + hstepB, voffB);
;             PG8_WAIT_V(6); PG8_BAR; PG8_MMA(1, 1, At, B1); PG8_BAR;
;     __device__ __forceinline__ void operator()(const AccT& acc, const Unit& u, int wr, int wc, int fr, int fq) const {
; #pragma unroll
;         for (int bj = 0; bj < 2; ++bj) {
;             const int col = u.pn * 256 + bj * 128 + wc * 32 + 8 * fq;
;             const f32x4 b0 = *(const f32x4*)(bias + col), b1 = *(const f32x4*)(bias + col + 4);
; #pragma unroll
;             for (int ai = 0; ai < 2; ++ai)
; #pragma unroll
;                 for (int m = 0; m < 4; ++m) {
;                     const int row = u.pm * 256 + ai * 128 + wr * 64 + m * 16 + fr;
;                     const u32x4 y = *(const u32x4*)(Y + (size_t)row * 1024 + col);
	s_waitcnt lgkmcnt(0)
	s_setprio 1
	s_waitcnt lgkmcnt(0)
	v_mfma_f32_16x16x32_bf16 v[94:97], v[122:125], v[194:197], v[94:97]
	v_mfma_f32_16x16x32_bf16 v[90:93], v[166:169], v[194:197], v[90:93]
	v_mfma_f32_16x16x32_bf16 v[86:89], v[122:125], v[202:205], v[86:89]
	v_mfma_f32_16x16x32_bf16 v[82:85], v[166:169], v[202:205], v[82:85]
	v_mfma_f32_16x16x32_bf16 v[78:81], v[122:125], v[210:213], v[78:81]
	v_mfma_f32_16x16x32_bf16 v[74:77], v[166:169], v[210:213], v[74:77]
	v_mfma_f32_16x16x32_bf16 v[46:49], v[122:125], v[218:221], v[46:49]
	v_mfma_f32_16x16x32_bf16 v[42:45], v[166:169], v[218:221], v[42:45]
	v_mfma_f32_16x16x32_bf16 v[94:97], v[126:129], v[198:201], v[94:97]
	v_mfma_f32_16x16x32_bf16 v[90:93], v[170:173], v[198:201], v[90:93]
	v_mfma_f32_16x16x32_bf16 v[86:89], v[126:129], v[206:209], v[86:89]
	v_mfma_f32_16x16x32_bf16 v[82:85], v[170:173], v[206:209], v[82:85]
	v_mfma_f32_16x16x32_bf16 v[78:81], v[126:129], v[214:217], v[78:81]
	v_mfma_f32_16x16x32_bf16 v[74:77], v[170:173], v[214:217], v[74:77]
	v_mfma_f32_16x16x32_bf16 v[46:49], v[126:129], v[222:225], v[46:49]
	v_mfma_f32_16x16x32_bf16 v[42:45], v[170:173], v[222:225], v[42:45]
	s_setprio 0
	s_barrier
	s_add_u32 s20, s20, 0x40080
	s_addc_u32 s21, s21, 0
	s_add_i32 s22, s22, s28
	v_lshl_add_u64 v[122:123], s[20:21], 0, v[0:1]
	s_mov_b32 m0, s22
	s_nop 0
	global_load_lds_dwordx4 v[122:123], off
	v_lshl_add_u64 v[122:123], s[20:21], 0, v[156:157]
	s_add_i32 m0, s22, 0x2000
	s_nop 0
	global_load_lds_dwordx4 v[122:123], off
	s_waitcnt vmcnt(6)
	s_barrier
	s_setprio 1
	v_mfma_f32_16x16x32_bf16 v[30:33], v[226:229], v[194:197], v[30:33]
	v_mfma_f32_16x16x32_bf16 v[26:29], v[234:237], v[194:197], v[26:29]
	v_mfma_f32_16x16x32_bf16 v[22:25], v[226:229], v[202:205], v[22:25]
	v_mfma_f32_16x16x32_bf16 v[18:21], v[234:237], v[202:205], v[18:21]
	v_mfma_f32_16x16x32_bf16 v[14:17], v[226:229], v[210:213], v[14:17]
	v_mfma_f32_16x16x32_bf16 v[10:13], v[234:237], v[210:213], v[10:13]
	v_mfma_f32_16x16x32_bf16 v[6:9], v[226:229], v[218:221], v[6:9]
	v_mfma_f32_16x16x32_bf16 v[2:5], v[234:237], v[218:221], v[2:5]
	v_mfma_f32_16x16x32_bf16 v[30:33], v[230:233], v[198:201], v[30:33]
	v_mfma_f32_16x16x32_bf16 v[26:29], v[238:241], v[198:201], v[26:29]
	v_mfma_f32_16x16x32_bf16 v[22:25], v[230:233], v[206:209], v[22:25]
	v_mfma_f32_16x16x32_bf16 v[18:21], v[238:241], v[206:209], v[18:21]
	v_mfma_f32_16x16x32_bf16 v[14:17], v[230:233], v[214:217], v[14:17]
	v_mfma_f32_16x16x32_bf16 v[10:13], v[238:241], v[214:217], v[10:13]
	v_mfma_f32_16x16x32_bf16 v[6:9], v[230:233], v[222:225], v[6:9]
	v_mfma_f32_16x16x32_bf16 v[2:5], v[238:241], v[222:225], v[2:5]
	s_setprio 0
	s_add_i32 s48, s48, 2
	s_add_u32 s18, s18, 0x100
	s_addc_u32 s19, s19, 0
	s_add_u32 s46, s46, 0x100
	s_addc_u32 s47, s47, 0
	s_cmp_gt_u32 s48, 13
	s_barrier
	s_cbranch_scc0 .LBB0_759
	v_lshl_or_b32 v242, s41, 8, v175
	v_ashrrev_i32_e32 v243, 31, v242
	v_lshl_add_u32 v244, s40, 8, v139
	v_ashrrev_i32_e32 v245, 31, v244
	v_lshlrev_b64 v[244:245], 11, v[244:245]
	v_lshl_add_u64 v[246:247], v[242:243], 2, s[8:9]
	v_lshl_add_u64 v[244:245], v[242:243], 1, v[244:245]
	v_lshl_add_u64 v[248:249], s[0:1], 0, v[244:245]
	v_lshl_add_u64 v[244:245], s[6:7], 0, v[244:245]
	s_mov_b32 s41, s10
	s_mov_b32 s40, s12
	s_mov_b64 s[20:21], s[16:17]
	s_mov_b64 s[18:19], s[14:15]
	global_load_dwordx4 v[226:229], v[246:247], off
	global_load_dwordx4 v[230:233], v[246:247], off offset:16
	global_load_dwordx4 v[194:197], v[248:249], off
	s_mov_b64 vcc, 0x8000
	v_lshl_add_u64 v[242:243], v[248:249], 0, vcc
	global_load_dwordx4 v[198:201], v[242:243], off
	s_mov_b64 vcc, 0x10000
	v_lshl_add_u64 v[250:251], v[248:249], 0, vcc
	global_load_dwordx4 v[202:205], v[250:251], off
	s_mov_b64 vcc, 0x18000
	v_lshl_add_u64 v[242:243], v[248:249], 0, vcc
	global_load_dwordx4 v[206:209], v[242:243], off
	s_mov_b64 vcc, 0x40000
	v_lshl_add_u64 v[250:251], v[248:249], 0, vcc
	global_load_dwordx4 v[210:213], v[250:251], off
	s_mov_b64 vcc, 0x48000
	v_lshl_add_u64 v[242:243], v[248:249], 0, vcc
	global_load_dwordx4 v[214:217], v[242:243], off
	s_mov_b64 vcc, 0x50000
	v_lshl_add_u64 v[250:251], v[248:249], 0, vcc
	global_load_dwordx4 v[218:221], v[250:251], off
	s_mov_b64 vcc, 0x58000
	v_lshl_add_u64 v[242:243], v[248:249], 0, vcc
	global_load_dwordx4 v[222:225], v[242:243], off
	s_waitcnt vmcnt(0)
; __device__ __forceinline__ unsigned cvt_pk_bf16(float lo, float hi) { const f32x2 v = {lo, hi}; const bf16x2_t b = __builtin_convertvector(v, bf16x2_t); return __builtin_bit_cast(unsigned, b); }
; __device__ __forceinline__ float bflo(unsigned u) { return __uint_as_float(u << 16); }
; __device__ __forceinline__ float bfhi(unsigned u) { return __uint_as_float(u & 0xffff0000u); }
; __device__ __forceinline__ float sigmoidf_(float x) { return __builtin_amdgcn_rcpf(1.0f + __expf(-x)); }
;     __device__ __forceinline__ void operator()(const AccT& acc, const Unit& u, int wr, int wc, int fr, int fq) const {
;     ...
;         for (int bj = 0; bj < 2; ++bj) {
;             const int col = u.pn * 256 + bj * 128 + wc * 32 + 8 * fq;
;             const f32x4 b0 = *(const f32x4*)(bias + col), b1 = *(const f32x4*)(bias + col + 4);
; #pragma unroll
;             for (int ai = 0; ai < 2; ++ai)
; #pragma unroll
;                 for (int m = 0; m < 4; ++m) {
;                     const int row = u.pm * 256 + ai * 128 + wr * 64 + m * 16 + fr;
;                     const u32x4 y = *(const u32x4*)(Y + (size_t)row * 1024 + col);
;                     const f32x4 v0 = acc[ai][bj][m][0] + b0, v1 = acc[ai][bj][m][1] + b1;
;                     u32x4 w;
;                     w.x = cvt_pk_bf16(bflo(y.x) * sigmoidf_(v0[0]), bfhi(y.x) * sigmoidf_(v0[1]));
;                     w.y = cvt_pk_bf16(bflo(y.y) * sigmoidf_(v0[2]), bfhi(y.y) * sigmoidf_(v0[3]));
;                     w.z = cvt_pk_bf16(bflo(y.z) * sigmoidf_(v1[0]), bfhi(y.z) * sigmoidf_(v1[1]));
;                     w.w = cvt_pk_bf16(bflo(y.w) * sigmoidf_(v1[2]), bfhi(y.w) * sigmoidf_(v1[3]));
;                     *(u32x4*)(O + (size_t)row * 1024 + col) = w;
	v_pk_add_f32 v[134:135], v[134:135], v[226:227]
	v_pk_add_f32 v[136:137], v[136:137], v[228:229]
	v_pk_add_f32 v[130:131], v[130:131], v[230:231]
	v_pk_add_f32 v[132:133], v[132:133], v[232:233]
	v_mul_f32_e32 v134, 0xbfb8aa3b, v134
	v_mul_f32_e32 v135, 0xbfb8aa3b, v135
	v_mul_f32_e32 v136, 0xbfb8aa3b, v136
	v_mul_f32_e32 v137, 0xbfb8aa3b, v137
	v_mul_f32_e32 v130, 0xbfb8aa3b, v130
	v_mul_f32_e32 v131, 0xbfb8aa3b, v131
	v_mul_f32_e32 v132, 0xbfb8aa3b, v132
	v_mul_f32_e32 v133, 0xbfb8aa3b, v133
	v_exp_f32_e32 v134, v134
	v_exp_f32_e32 v135, v135
	v_exp_f32_e32 v136, v136
	v_exp_f32_e32 v137, v137
	v_exp_f32_e32 v130, v130
	v_exp_f32_e32 v131, v131
	v_exp_f32_e32 v132, v132
	v_exp_f32_e32 v133, v133
	v_add_f32_e32 v134, 1.0, v134
	v_add_f32_e32 v135, 1.0, v135
	v_add_f32_e32 v136, 1.0, v136
	v_add_f32_e32 v137, 1.0, v137
	v_add_f32_e32 v130, 1.0, v130
	v_add_f32_e32 v131, 1.0, v131
	v_add_f32_e32 v132, 1.0, v132
	v_add_f32_e32 v133, 1.0, v133
	v_rcp_f32_e32 v134, v134
	v_rcp_f32_e32 v135, v135
	v_rcp_f32_e32 v136, v136
	v_rcp_f32_e32 v137, v137
	v_rcp_f32_e32 v130, v130
	v_rcp_f32_e32 v131, v131
	v_rcp_f32_e32 v132, v132
	v_rcp_f32_e32 v133, v133
	v_lshlrev_b32_e32 v234, 16, v194
	v_and_b32_e32 v235, 0xffff0000, v194
	v_lshlrev_b32_e32 v236, 16, v195
	v_and_b32_e32 v237, 0xffff0000, v195
	v_pk_mul_f32 v[134:135], v[134:135], v[234:235]
	v_pk_mul_f32 v[136:137], v[136:137], v[236:237]
	v_lshlrev_b32_e32 v234, 16, v196
	v_and_b32_e32 v235, 0xffff0000, v196
	v_lshlrev_b32_e32 v236, 16, v197
	v_and_b32_e32 v237, 0xffff0000, v197
	v_pk_mul_f32 v[130:131], v[130:131], v[234:235]
	v_pk_mul_f32 v[132:133], v[132:133], v[236:237]
	s_nop 0
	v_cvt_pk_bf16_f32 v194, v134, v135
	v_cvt_pk_bf16_f32 v195, v136, v137
	v_cvt_pk_bf16_f32 v196, v130, v131
	v_cvt_pk_bf16_f32 v197, v132, v133
	global_store_dwordx4 v[244:245], v[194:197], off
	v_pk_add_f32 v[118:119], v[118:119], v[226:227]
	v_pk_add_f32 v[120:121], v[120:121], v[228:229]
	v_pk_add_f32 v[114:115], v[114:115], v[230:231]
	v_pk_add_f32 v[116:117], v[116:117], v[232:233]
	v_mul_f32_e32 v118, 0xbfb8aa3b, v118
	v_mul_f32_e32 v119, 0xbfb8aa3b, v119
	v_mul_f32_e32 v120, 0xbfb8aa3b, v120
	v_mul_f32_e32 v121, 0xbfb8aa3b, v121
	v_mul_f32_e32 v114, 0xbfb8aa3b, v114
	v_mul_f32_e32 v115, 0xbfb8aa3b, v115
	v_mul_f32_e32 v116, 0xbfb8aa3b, v116
	v_mul_f32_e32 v117, 0xbfb8aa3b, v117
	v_exp_f32_e32 v118, v118
	v_exp_f32_e32 v119, v119
	v_exp_f32_e32 v120, v120
	v_exp_f32_e32 v121, v121
	v_exp_f32_e32 v114, v114
	v_exp_f32_e32 v115, v115
	v_exp_f32_e32 v116, v116
	v_exp_f32_e32 v117, v117
	v_add_f32_e32 v118, 1.0, v118
	v_add_f32_e32 v119, 1.0, v119
	v_add_f32_e32 v120, 1.0, v120
	v_add_f32_e32 v121, 1.0, v121
	v_add_f32_e32 v114, 1.0, v114
	v_add_f32_e32 v115, 1.0, v115
	v_add_f32_e32 v116, 1.0, v116
	v_add_f32_e32 v117, 1.0, v117
	v_rcp_f32_e32 v118, v118
	v_rcp_f32_e32 v119, v119
	v_rcp_f32_e32 v120, v120
	v_rcp_f32_e32 v121, v121
	v_rcp_f32_e32 v114, v114
	v_rcp_f32_e32 v115, v115
	v_rcp_f32_e32 v116, v116
	v_rcp_f32_e32 v117, v117
	v_lshlrev_b32_e32 v234, 16, v198
	v_and_b32_e32 v235, 0xffff0000, v198
	v_lshlrev_b32_e32 v236, 16, v199
	v_and_b32_e32 v237, 0xffff0000, v199
	v_pk_mul_f32 v[118:119], v[118:119], v[234:235]
	v_pk_mul_f32 v[120:121], v[120:121], v[236:237]
	v_lshlrev_b32_e32 v234, 16, v200
	v_and_b32_e32 v235, 0xffff0000, v200
	v_lshlrev_b32_e32 v236, 16, v201
	v_and_b32_e32 v237, 0xffff0000, v201
	v_pk_mul_f32 v[114:115], v[114:115], v[234:235]
	v_pk_mul_f32 v[116:117], v[116:117], v[236:237]
	s_nop 0
	v_cvt_pk_bf16_f32 v198, v118, v119
	v_cvt_pk_bf16_f32 v199, v120, v121
	v_cvt_pk_bf16_f32 v200, v114, v115
	v_cvt_pk_bf16_f32 v201, v116, v117
	s_mov_b64 vcc, 0x8000
	v_lshl_add_u64 v[242:243], v[244:245], 0, vcc
	global_store_dwordx4 v[242:243], v[198:201], off
	v_pk_add_f32 v[110:111], v[110:111], v[226:227]
	v_pk_add_f32 v[112:113], v[112:113], v[228:229]
	v_pk_add_f32 v[106:107], v[106:107], v[230:231]
	v_pk_add_f32 v[108:109], v[108:109], v[232:233]
	v_mul_f32_e32 v110, 0xbfb8aa3b, v110
	v_mul_f32_e32 v111, 0xbfb8aa3b, v111
	v_mul_f32_e32 v112, 0xbfb8aa3b, v112
	v_mul_f32_e32 v113, 0xbfb8aa3b, v113
	v_mul_f32_e32 v106, 0xbfb8aa3b, v106
	v_mul_f32_e32 v107, 0xbfb8aa3b, v107
	v_mul_f32_e32 v108, 0xbfb8aa3b, v108
	v_mul_f32_e32 v109, 0xbfb8aa3b, v109
	v_exp_f32_e32 v110, v110
	v_exp_f32_e32 v111, v111
	v_exp_f32_e32 v112, v112
	v_exp_f32_e32 v113, v113
	v_exp_f32_e32 v106, v106
	v_exp_f32_e32 v107, v107
	v_exp_f32_e32 v108, v108
	v_exp_f32_e32 v109, v109
	v_add_f32_e32 v110, 1.0, v110
	v_add_f32_e32 v111, 1.0, v111
	v_add_f32_e32 v112, 1.0, v112
	v_add_f32_e32 v113, 1.0, v113
	v_add_f32_e32 v106, 1.0, v106
	v_add_f32_e32 v107, 1.0, v107
	v_add_f32_e32 v108, 1.0, v108
	v_add_f32_e32 v109, 1.0, v109
	v_rcp_f32_e32 v110, v110
	v_rcp_f32_e32 v111, v111
	v_rcp_f32_e32 v112, v112
	v_rcp_f32_e32 v113, v113
	v_rcp_f32_e32 v106, v106
	v_rcp_f32_e32 v107, v107
	v_rcp_f32_e32 v108, v108
	v_rcp_f32_e32 v109, v109
	v_lshlrev_b32_e32 v234, 16, v202
	v_and_b32_e32 v235, 0xffff0000, v202
	v_lshlrev_b32_e32 v236, 16, v203
	v_and_b32_e32 v237, 0xffff0000, v203
	v_pk_mul_f32 v[110:111], v[110:111], v[234:235]
	v_pk_mul_f32 v[112:113], v[112:113], v[236:237]
	v_lshlrev_b32_e32 v234, 16, v204
	v_and_b32_e32 v235, 0xffff0000, v204
	v_lshlrev_b32_e32 v236, 16, v205
	v_and_b32_e32 v237, 0xffff0000, v205
	v_pk_mul_f32 v[106:107], v[106:107], v[234:235]
	v_pk_mul_f32 v[108:109], v[108:109], v[236:237]
	s_nop 0
	v_cvt_pk_bf16_f32 v202, v110, v111
	v_cvt_pk_bf16_f32 v203, v112, v113
	v_cvt_pk_bf16_f32 v204, v106, v107
	v_cvt_pk_bf16_f32 v205, v108, v109
	s_mov_b64 vcc, 0x10000
	v_lshl_add_u64 v[250:251], v[244:245], 0, vcc
; __device__ __forceinline__ unsigned cvt_pk_bf16(float lo, float hi) { const f32x2 v = {lo, hi}; const bf16x2_t b = __builtin_convertvector(v, bf16x2_t); return __builtin_bit_cast(unsigned, b); }
; __device__ __forceinline__ float bflo(unsigned u) { return __uint_as_float(u << 16); }
; __device__ __forceinline__ float bfhi(unsigned u) { return __uint_as_float(u & 0xffff0000u); }
; __device__ __forceinline__ float sigmoidf_(float x) { return __builtin_amdgcn_rcpf(1.0f + __expf(-x)); }
;     __device__ __forceinline__ void operator()(const AccT& acc, const Unit& u, int wr, int wc, int fr, int fq) const {
;     ...
;         for (int bj = 0; bj < 2; ++bj) {
;             const int col = u.pn * 256 + bj * 128 + wc * 32 + 8 * fq;
;             const f32x4 b0 = *(const f32x4*)(bias + col), b1 = *(const f32x4*)(bias + col + 4);
; #pragma unroll
;             for (int ai = 0; ai < 2; ++ai)
; #pragma unroll
;                 for (int m = 0; m < 4; ++m) {
;                     const int row = u.pm * 256 + ai * 128 + wr * 64 + m * 16 + fr;
;                     const u32x4 y = *(const u32x4*)(Y + (size_t)row * 1024 + col);
;                     const f32x4 v0 = acc[ai][bj][m][0] + b0, v1 = acc[ai][bj][m][1] + b1;
;                     u32x4 w;
;                     w.x = cvt_pk_bf16(bflo(y.x) * sigmoidf_(v0[0]), bfhi(y.x) * sigmoidf_(v0[1]));
;                     w.y = cvt_pk_bf16(bflo(y.y) * sigmoidf_(v0[2]), bfhi(y.y) * sigmoidf_(v0[3]));
;                     w.z = cvt_pk_bf16(bflo(y.z) * sigmoidf_(v1[0]), bfhi(y.z) * sigmoidf_(v1[1]));
;                     w.w = cvt_pk_bf16(bflo(y.w) * sigmoidf_(v1[2]), bfhi(y.w) * sigmoidf_(v1[3]));
;                     *(u32x4*)(O + (size_t)row * 1024 + col) = w;
	global_store_dwordx4 v[250:251], v[202:205], off
	v_pk_add_f32 v[102:103], v[102:103], v[226:227]
	v_pk_add_f32 v[104:105], v[104:105], v[228:229]
	v_pk_add_f32 v[98:99], v[98:99], v[230:231]
	v_pk_add_f32 v[100:101], v[100:101], v[232:233]
	v_mul_f32_e32 v102, 0xbfb8aa3b, v102
	v_mul_f32_e32 v103, 0xbfb8aa3b, v103
	v_mul_f32_e32 v104, 0xbfb8aa3b, v104
	v_mul_f32_e32 v105, 0xbfb8aa3b, v105
	v_mul_f32_e32 v98, 0xbfb8aa3b, v98
	v_mul_f32_e32 v99, 0xbfb8aa3b, v99
	v_mul_f32_e32 v100, 0xbfb8aa3b, v100
	v_mul_f32_e32 v101, 0xbfb8aa3b, v101
	v_exp_f32_e32 v102, v102
	v_exp_f32_e32 v103, v103
	v_exp_f32_e32 v104, v104
	v_exp_f32_e32 v105, v105
	v_exp_f32_e32 v98, v98
	v_exp_f32_e32 v99, v99
	v_exp_f32_e32 v100, v100
	v_exp_f32_e32 v101, v101
	v_add_f32_e32 v102, 1.0, v102
	v_add_f32_e32 v103, 1.0, v103
	v_add_f32_e32 v104, 1.0, v104
	v_add_f32_e32 v105, 1.0, v105
	v_add_f32_e32 v98, 1.0, v98
	v_add_f32_e32 v99, 1.0, v99
	v_add_f32_e32 v100, 1.0, v100
	v_add_f32_e32 v101, 1.0, v101
	v_rcp_f32_e32 v102, v102
	v_rcp_f32_e32 v103, v103
	v_rcp_f32_e32 v104, v104
	v_rcp_f32_e32 v105, v105
	v_rcp_f32_e32 v98, v98
	v_rcp_f32_e32 v99, v99
	v_rcp_f32_e32 v100, v100
	v_rcp_f32_e32 v101, v101
	v_lshlrev_b32_e32 v234, 16, v206
	v_and_b32_e32 v235, 0xffff0000, v206
	v_lshlrev_b32_e32 v236, 16, v207
	v_and_b32_e32 v237, 0xffff0000, v207
	v_pk_mul_f32 v[102:103], v[102:103], v[234:235]
	v_pk_mul_f32 v[104:105], v[104:105], v[236:237]
	v_lshlrev_b32_e32 v234, 16, v208
	v_and_b32_e32 v235, 0xffff0000, v208
	v_lshlrev_b32_e32 v236, 16, v209
	v_and_b32_e32 v237, 0xffff0000, v209
	v_pk_mul_f32 v[98:99], v[98:99], v[234:235]
	v_pk_mul_f32 v[100:101], v[100:101], v[236:237]
	s_nop 0
	v_cvt_pk_bf16_f32 v206, v102, v103
	v_cvt_pk_bf16_f32 v207, v104, v105
	v_cvt_pk_bf16_f32 v208, v98, v99
	v_cvt_pk_bf16_f32 v209, v100, v101
	s_mov_b64 vcc, 0x18000
	v_lshl_add_u64 v[242:243], v[244:245], 0, vcc
	global_store_dwordx4 v[242:243], v[206:209], off
	v_pk_add_f32 v[94:95], v[94:95], v[226:227]
	v_pk_add_f32 v[96:97], v[96:97], v[228:229]
	v_pk_add_f32 v[90:91], v[90:91], v[230:231]
	v_pk_add_f32 v[92:93], v[92:93], v[232:233]
	v_mul_f32_e32 v94, 0xbfb8aa3b, v94
	v_mul_f32_e32 v95, 0xbfb8aa3b, v95
	v_mul_f32_e32 v96, 0xbfb8aa3b, v96
	v_mul_f32_e32 v97, 0xbfb8aa3b, v97
	v_mul_f32_e32 v90, 0xbfb8aa3b, v90
	v_mul_f32_e32 v91, 0xbfb8aa3b, v91
	v_mul_f32_e32 v92, 0xbfb8aa3b, v92
	v_mul_f32_e32 v93, 0xbfb8aa3b, v93
	v_exp_f32_e32 v94, v94
	v_exp_f32_e32 v95, v95
	v_exp_f32_e32 v96, v96
	v_exp_f32_e32 v97, v97
	v_exp_f32_e32 v90, v90
	v_exp_f32_e32 v91, v91
	v_exp_f32_e32 v92, v92
	v_exp_f32_e32 v93, v93
	v_add_f32_e32 v94, 1.0, v94
	v_add_f32_e32 v95, 1.0, v95
	v_add_f32_e32 v96, 1.0, v96
	v_add_f32_e32 v97, 1.0, v97
	v_add_f32_e32 v90, 1.0, v90
	v_add_f32_e32 v91, 1.0, v91
	v_add_f32_e32 v92, 1.0, v92
	v_add_f32_e32 v93, 1.0, v93
	v_rcp_f32_e32 v94, v94
	v_rcp_f32_e32 v95, v95
	v_rcp_f32_e32 v96, v96
	v_rcp_f32_e32 v97, v97
	v_rcp_f32_e32 v90, v90
	v_rcp_f32_e32 v91, v91
	v_rcp_f32_e32 v92, v92
	v_rcp_f32_e32 v93, v93
	v_lshlrev_b32_e32 v234, 16, v210
	v_and_b32_e32 v235, 0xffff0000, v210
	v_lshlrev_b32_e32 v236, 16, v211
	v_and_b32_e32 v237, 0xffff0000, v211
	v_pk_mul_f32 v[94:95], v[94:95], v[234:235]
	v_pk_mul_f32 v[96:97], v[96:97], v[236:237]
	v_lshlrev_b32_e32 v234, 16, v212
	v_and_b32_e32 v235, 0xffff0000, v212
	v_lshlrev_b32_e32 v236, 16, v213
	v_and_b32_e32 v237, 0xffff0000, v213
	v_pk_mul_f32 v[90:91], v[90:91], v[234:235]
	v_pk_mul_f32 v[92:93], v[92:93], v[236:237]
	s_nop 0
	v_cvt_pk_bf16_f32 v210, v94, v95
	v_cvt_pk_bf16_f32 v211, v96, v97
	v_cvt_pk_bf16_f32 v212, v90, v91
	v_cvt_pk_bf16_f32 v213, v92, v93
	s_mov_b64 vcc, 0x40000
	v_lshl_add_u64 v[250:251], v[244:245], 0, vcc
	global_store_dwordx4 v[250:251], v[210:213], off
	v_pk_add_f32 v[86:87], v[86:87], v[226:227]
	v_pk_add_f32 v[88:89], v[88:89], v[228:229]
	v_pk_add_f32 v[82:83], v[82:83], v[230:231]
	v_pk_add_f32 v[84:85], v[84:85], v[232:233]
	v_mul_f32_e32 v86, 0xbfb8aa3b, v86
	v_mul_f32_e32 v87, 0xbfb8aa3b, v87
	v_mul_f32_e32 v88, 0xbfb8aa3b, v88
	v_mul_f32_e32 v89, 0xbfb8aa3b, v89
	v_mul_f32_e32 v82, 0xbfb8aa3b, v82
	v_mul_f32_e32 v83, 0xbfb8aa3b, v83
	v_mul_f32_e32 v84, 0xbfb8aa3b, v84
	v_mul_f32_e32 v85, 0xbfb8aa3b, v85
	v_exp_f32_e32 v86, v86
	v_exp_f32_e32 v87, v87
	v_exp_f32_e32 v88, v88
	v_exp_f32_e32 v89, v89
	v_exp_f32_e32 v82, v82
	v_exp_f32_e32 v83, v83
	v_exp_f32_e32 v84, v84
	v_exp_f32_e32 v85, v85
	v_add_f32_e32 v86, 1.0, v86
	v_add_f32_e32 v87, 1.0, v87
	v_add_f32_e32 v88, 1.0, v88
	v_add_f32_e32 v89, 1.0, v89
	v_add_f32_e32 v82, 1.0, v82
	v_add_f32_e32 v83, 1.0, v83
	v_add_f32_e32 v84, 1.0, v84
	v_add_f32_e32 v85, 1.0, v85
	v_rcp_f32_e32 v86, v86
	v_rcp_f32_e32 v87, v87
	v_rcp_f32_e32 v88, v88
	v_rcp_f32_e32 v89, v89
	v_rcp_f32_e32 v82, v82
	v_rcp_f32_e32 v83, v83
	v_rcp_f32_e32 v84, v84
	v_rcp_f32_e32 v85, v85
	v_lshlrev_b32_e32 v234, 16, v214
	v_and_b32_e32 v235, 0xffff0000, v214
	v_lshlrev_b32_e32 v236, 16, v215
	v_and_b32_e32 v237, 0xffff0000, v215
	v_pk_mul_f32 v[86:87], v[86:87], v[234:235]
	v_pk_mul_f32 v[88:89], v[88:89], v[236:237]
	v_lshlrev_b32_e32 v234, 16, v216
	v_and_b32_e32 v235, 0xffff0000, v216
	v_lshlrev_b32_e32 v236, 16, v217
	v_and_b32_e32 v237, 0xffff0000, v217
	v_pk_mul_f32 v[82:83], v[82:83], v[234:235]
	v_pk_mul_f32 v[84:85], v[84:85], v[236:237]
	s_nop 0
	v_cvt_pk_bf16_f32 v214, v86, v87
	v_cvt_pk_bf16_f32 v215, v88, v89
	v_cvt_pk_bf16_f32 v216, v82, v83
	v_cvt_pk_bf16_f32 v217, v84, v85
	s_mov_b64 vcc, 0x48000
	v_lshl_add_u64 v[242:243], v[244:245], 0, vcc
	global_store_dwordx4 v[242:243], v[214:217], off
	v_pk_add_f32 v[78:79], v[78:79], v[226:227]
; __device__ __forceinline__ unsigned cvt_pk_bf16(float lo, float hi) { const f32x2 v = {lo, hi}; const bf16x2_t b = __builtin_convertvector(v, bf16x2_t); return __builtin_bit_cast(unsigned, b); }
; __device__ __forceinline__ float bflo(unsigned u) { return __uint_as_float(u << 16); }
; __device__ __forceinline__ float bfhi(unsigned u) { return __uint_as_float(u & 0xffff0000u); }
; __device__ __forceinline__ float sigmoidf_(float x) { return __builtin_amdgcn_rcpf(1.0f + __expf(-x)); }
;     __device__ __forceinline__ void operator()(const AccT& acc, const Unit& u, int wr, int wc, int fr, int fq) const {
;     ...
;         for (int bj = 0; bj < 2; ++bj) {
;             const int col = u.pn * 256 + bj * 128 + wc * 32 + 8 * fq;
;             const f32x4 b0 = *(const f32x4*)(bias + col), b1 = *(const f32x4*)(bias + col + 4);
; #pragma unroll
;             for (int ai = 0; ai < 2; ++ai)
; #pragma unroll
;                 for (int m = 0; m < 4; ++m) {
;                     const int row = u.pm * 256 + ai * 128 + wr * 64 + m * 16 + fr;
;                     const u32x4 y = *(const u32x4*)(Y + (size_t)row * 1024 + col);
;                     const f32x4 v0 = acc[ai][bj][m][0] + b0, v1 = acc[ai][bj][m][1] + b1;
;                     u32x4 w;
;                     w.x = cvt_pk_bf16(bflo(y.x) * sigmoidf_(v0[0]), bfhi(y.x) * sigmoidf_(v0[1]));
;                     w.y = cvt_pk_bf16(bflo(y.y) * sigmoidf_(v0[2]), bfhi(y.y) * sigmoidf_(v0[3]));
;                     w.z = cvt_pk_bf16(bflo(y.z) * sigmoidf_(v1[0]), bfhi(y.z) * sigmoidf_(v1[1]));
;                     w.w = cvt_pk_bf16(bflo(y.w) * sigmoidf_(v1[2]), bfhi(y.w) * sigmoidf_(v1[3]));
;                     *(u32x4*)(O + (size_t)row * 1024 + col) = w;
	v_pk_add_f32 v[80:81], v[80:81], v[228:229]
	v_pk_add_f32 v[74:75], v[74:75], v[230:231]
	v_pk_add_f32 v[76:77], v[76:77], v[232:233]
	v_mul_f32_e32 v78, 0xbfb8aa3b, v78
	v_mul_f32_e32 v79, 0xbfb8aa3b, v79
	v_mul_f32_e32 v80, 0xbfb8aa3b, v80
	v_mul_f32_e32 v81, 0xbfb8aa3b, v81
	v_mul_f32_e32 v74, 0xbfb8aa3b, v74
	v_mul_f32_e32 v75, 0xbfb8aa3b, v75
	v_mul_f32_e32 v76, 0xbfb8aa3b, v76
	v_mul_f32_e32 v77, 0xbfb8aa3b, v77
	v_exp_f32_e32 v78, v78
	v_exp_f32_e32 v79, v79
	v_exp_f32_e32 v80, v80
	v_exp_f32_e32 v81, v81
	v_exp_f32_e32 v74, v74
	v_exp_f32_e32 v75, v75
	v_exp_f32_e32 v76, v76
	v_exp_f32_e32 v77, v77
	v_add_f32_e32 v78, 1.0, v78
	v_add_f32_e32 v79, 1.0, v79
	v_add_f32_e32 v80, 1.0, v80
	v_add_f32_e32 v81, 1.0, v81
	v_add_f32_e32 v74, 1.0, v74
	v_add_f32_e32 v75, 1.0, v75
	v_add_f32_e32 v76, 1.0, v76
	v_add_f32_e32 v77, 1.0, v77
	v_rcp_f32_e32 v78, v78
	v_rcp_f32_e32 v79, v79
	v_rcp_f32_e32 v80, v80
	v_rcp_f32_e32 v81, v81
	v_rcp_f32_e32 v74, v74
	v_rcp_f32_e32 v75, v75
	v_rcp_f32_e32 v76, v76
	v_rcp_f32_e32 v77, v77
	v_lshlrev_b32_e32 v234, 16, v218
	v_and_b32_e32 v235, 0xffff0000, v218
	v_lshlrev_b32_e32 v236, 16, v219
	v_and_b32_e32 v237, 0xffff0000, v219
	v_pk_mul_f32 v[78:79], v[78:79], v[234:235]
	v_pk_mul_f32 v[80:81], v[80:81], v[236:237]
	v_lshlrev_b32_e32 v234, 16, v220
	v_and_b32_e32 v235, 0xffff0000, v220
	v_lshlrev_b32_e32 v236, 16, v221
	v_and_b32_e32 v237, 0xffff0000, v221
	v_pk_mul_f32 v[74:75], v[74:75], v[234:235]
	v_pk_mul_f32 v[76:77], v[76:77], v[236:237]
	s_nop 0
	v_cvt_pk_bf16_f32 v218, v78, v79
	v_cvt_pk_bf16_f32 v219, v80, v81
	v_cvt_pk_bf16_f32 v220, v74, v75
	v_cvt_pk_bf16_f32 v221, v76, v77
	s_mov_b64 vcc, 0x50000
	v_lshl_add_u64 v[250:251], v[244:245], 0, vcc
	global_store_dwordx4 v[250:251], v[218:221], off
	v_pk_add_f32 v[46:47], v[46:47], v[226:227]
	v_pk_add_f32 v[48:49], v[48:49], v[228:229]
	v_pk_add_f32 v[42:43], v[42:43], v[230:231]
	v_pk_add_f32 v[44:45], v[44:45], v[232:233]
	v_mul_f32_e32 v46, 0xbfb8aa3b, v46
	v_mul_f32_e32 v47, 0xbfb8aa3b, v47
	v_mul_f32_e32 v48, 0xbfb8aa3b, v48
	v_mul_f32_e32 v49, 0xbfb8aa3b, v49
	v_mul_f32_e32 v42, 0xbfb8aa3b, v42
	v_mul_f32_e32 v43, 0xbfb8aa3b, v43
	v_mul_f32_e32 v44, 0xbfb8aa3b, v44
	v_mul_f32_e32 v45, 0xbfb8aa3b, v45
	v_exp_f32_e32 v46, v46
	v_exp_f32_e32 v47, v47
	v_exp_f32_e32 v48, v48
	v_exp_f32_e32 v49, v49
	v_exp_f32_e32 v42, v42
	v_exp_f32_e32 v43, v43
	v_exp_f32_e32 v44, v44
	v_exp_f32_e32 v45, v45
	v_add_f32_e32 v46, 1.0, v46
	v_add_f32_e32 v47, 1.0, v47
	v_add_f32_e32 v48, 1.0, v48
	v_add_f32_e32 v49, 1.0, v49
	v_add_f32_e32 v42, 1.0, v42
	v_add_f32_e32 v43, 1.0, v43
	v_add_f32_e32 v44, 1.0, v44
	v_add_f32_e32 v45, 1.0, v45
	v_rcp_f32_e32 v46, v46
	v_rcp_f32_e32 v47, v47
	v_rcp_f32_e32 v48, v48
	v_rcp_f32_e32 v49, v49
	v_rcp_f32_e32 v42, v42
	v_rcp_f32_e32 v43, v43
	v_rcp_f32_e32 v44, v44
	v_rcp_f32_e32 v45, v45
	v_lshlrev_b32_e32 v234, 16, v222
	v_and_b32_e32 v235, 0xffff0000, v222
	v_lshlrev_b32_e32 v236, 16, v223
	v_and_b32_e32 v237, 0xffff0000, v223
	v_pk_mul_f32 v[46:47], v[46:47], v[234:235]
	v_pk_mul_f32 v[48:49], v[48:49], v[236:237]
	v_lshlrev_b32_e32 v234, 16, v224
	v_and_b32_e32 v235, 0xffff0000, v224
	v_lshlrev_b32_e32 v236, 16, v225
	v_and_b32_e32 v237, 0xffff0000, v225
	v_pk_mul_f32 v[42:43], v[42:43], v[234:235]
	v_pk_mul_f32 v[44:45], v[44:45], v[236:237]
	s_nop 0
	v_cvt_pk_bf16_f32 v222, v46, v47
	v_cvt_pk_bf16_f32 v223, v48, v49
	v_cvt_pk_bf16_f32 v224, v42, v43
	v_cvt_pk_bf16_f32 v225, v44, v45
	s_mov_b64 vcc, 0x58000
	v_lshl_add_u64 v[242:243], v[244:245], 0, vcc
	global_store_dwordx4 v[242:243], v[222:225], off
	global_load_dwordx4 v[226:229], v[246:247], off offset:512
	global_load_dwordx4 v[230:233], v[246:247], off offset:528
	global_load_dwordx4 v[194:197], v[248:249], off offset:256
	s_mov_b64 vcc, 0x8000
	v_lshl_add_u64 v[242:243], v[248:249], 0, vcc
	global_load_dwordx4 v[198:201], v[242:243], off offset:256
	s_mov_b64 vcc, 0x10000
	v_lshl_add_u64 v[250:251], v[248:249], 0, vcc
	global_load_dwordx4 v[202:205], v[250:251], off offset:256
	s_mov_b64 vcc, 0x18000
	v_lshl_add_u64 v[242:243], v[248:249], 0, vcc
	global_load_dwordx4 v[206:209], v[242:243], off offset:256
	s_mov_b64 vcc, 0x40000
	v_lshl_add_u64 v[250:251], v[248:249], 0, vcc
	global_load_dwordx4 v[210:213], v[250:251], off offset:256
	s_mov_b64 vcc, 0x48000
	v_lshl_add_u64 v[242:243], v[248:249], 0, vcc
	global_load_dwordx4 v[214:217], v[242:243], off offset:256
	s_mov_b64 vcc, 0x50000
	v_lshl_add_u64 v[250:251], v[248:249], 0, vcc
	global_load_dwordx4 v[218:221], v[250:251], off offset:256
	s_mov_b64 vcc, 0x58000
	v_lshl_add_u64 v[242:243], v[248:249], 0, vcc
	global_load_dwordx4 v[222:225], v[242:243], off offset:256
	s_waitcnt vmcnt(0)
; __device__ __forceinline__ unsigned cvt_pk_bf16(float lo, float hi) { const f32x2 v = {lo, hi}; const bf16x2_t b = __builtin_convertvector(v, bf16x2_t); return __builtin_bit_cast(unsigned, b); }
; __device__ __forceinline__ float bflo(unsigned u) { return __uint_as_float(u << 16); }
; __device__ __forceinline__ float bfhi(unsigned u) { return __uint_as_float(u & 0xffff0000u); }
; __device__ __forceinline__ float sigmoidf_(float x) { return __builtin_amdgcn_rcpf(1.0f + __expf(-x)); }
;     __device__ __forceinline__ void operator()(const AccT& acc, const Unit& u, int wr, int wc, int fr, int fq) const {
;     ...
;         for (int bj = 0; bj < 2; ++bj) {
;             const int col = u.pn * 256 + bj * 128 + wc * 32 + 8 * fq;
;             const f32x4 b0 = *(const f32x4*)(bias + col), b1 = *(const f32x4*)(bias + col + 4);
; #pragma unroll
;             for (int ai = 0; ai < 2; ++ai)
; #pragma unroll
;                 for (int m = 0; m < 4; ++m) {
;                     const int row = u.pm * 256 + ai * 128 + wr * 64 + m * 16 + fr;
;                     const u32x4 y = *(const u32x4*)(Y + (size_t)row * 1024 + col);
;                     const f32x4 v0 = acc[ai][bj][m][0] + b0, v1 = acc[ai][bj][m][1] + b1;
;                     u32x4 w;
;                     w.x = cvt_pk_bf16(bflo(y.x) * sigmoidf_(v0[0]), bfhi(y.x) * sigmoidf_(v0[1]));
;                     w.y = cvt_pk_bf16(bflo(y.y) * sigmoidf_(v0[2]), bfhi(y.y) * sigmoidf_(v0[3]));
;                     w.z = cvt_pk_bf16(bflo(y.z) * sigmoidf_(v1[0]), bfhi(y.z) * sigmoidf_(v1[1]));
;                     w.w = cvt_pk_bf16(bflo(y.w) * sigmoidf_(v1[2]), bfhi(y.w) * sigmoidf_(v1[3]));
;                     *(u32x4*)(O + (size_t)row * 1024 + col) = w;
	v_pk_add_f32 v[70:71], v[70:71], v[226:227]
	v_pk_add_f32 v[72:73], v[72:73], v[228:229]
	v_pk_add_f32 v[66:67], v[66:67], v[230:231]
	v_pk_add_f32 v[68:69], v[68:69], v[232:233]
	v_mul_f32_e32 v70, 0xbfb8aa3b, v70
	v_mul_f32_e32 v71, 0xbfb8aa3b, v71
	v_mul_f32_e32 v72, 0xbfb8aa3b, v72
	v_mul_f32_e32 v73, 0xbfb8aa3b, v73
	v_mul_f32_e32 v66, 0xbfb8aa3b, v66
	v_mul_f32_e32 v67, 0xbfb8aa3b, v67
	v_mul_f32_e32 v68, 0xbfb8aa3b, v68
	v_mul_f32_e32 v69, 0xbfb8aa3b, v69
	v_exp_f32_e32 v70, v70
	v_exp_f32_e32 v71, v71
	v_exp_f32_e32 v72, v72
	v_exp_f32_e32 v73, v73
	v_exp_f32_e32 v66, v66
	v_exp_f32_e32 v67, v67
	v_exp_f32_e32 v68, v68
	v_exp_f32_e32 v69, v69
	v_add_f32_e32 v70, 1.0, v70
	v_add_f32_e32 v71, 1.0, v71
	v_add_f32_e32 v72, 1.0, v72
	v_add_f32_e32 v73, 1.0, v73
	v_add_f32_e32 v66, 1.0, v66
	v_add_f32_e32 v67, 1.0, v67
	v_add_f32_e32 v68, 1.0, v68
	v_add_f32_e32 v69, 1.0, v69
	v_rcp_f32_e32 v70, v70
	v_rcp_f32_e32 v71, v71
	v_rcp_f32_e32 v72, v72
	v_rcp_f32_e32 v73, v73
	v_rcp_f32_e32 v66, v66
	v_rcp_f32_e32 v67, v67
	v_rcp_f32_e32 v68, v68
	v_rcp_f32_e32 v69, v69
	v_lshlrev_b32_e32 v234, 16, v194
	v_and_b32_e32 v235, 0xffff0000, v194
	v_lshlrev_b32_e32 v236, 16, v195
	v_and_b32_e32 v237, 0xffff0000, v195
	v_pk_mul_f32 v[70:71], v[70:71], v[234:235]
	v_pk_mul_f32 v[72:73], v[72:73], v[236:237]
	v_lshlrev_b32_e32 v234, 16, v196
	v_and_b32_e32 v235, 0xffff0000, v196
	v_lshlrev_b32_e32 v236, 16, v197
	v_and_b32_e32 v237, 0xffff0000, v197
	v_pk_mul_f32 v[66:67], v[66:67], v[234:235]
	v_pk_mul_f32 v[68:69], v[68:69], v[236:237]
	s_nop 0
	v_cvt_pk_bf16_f32 v194, v70, v71
	v_cvt_pk_bf16_f32 v195, v72, v73
	v_cvt_pk_bf16_f32 v196, v66, v67
	v_cvt_pk_bf16_f32 v197, v68, v69
	global_store_dwordx4 v[244:245], v[194:197], off offset:256
	v_pk_add_f32 v[62:63], v[62:63], v[226:227]
	v_pk_add_f32 v[64:65], v[64:65], v[228:229]
	v_pk_add_f32 v[58:59], v[58:59], v[230:231]
	v_pk_add_f32 v[60:61], v[60:61], v[232:233]
	v_mul_f32_e32 v62, 0xbfb8aa3b, v62
	v_mul_f32_e32 v63, 0xbfb8aa3b, v63
	v_mul_f32_e32 v64, 0xbfb8aa3b, v64
	v_mul_f32_e32 v65, 0xbfb8aa3b, v65
	v_mul_f32_e32 v58, 0xbfb8aa3b, v58
	v_mul_f32_e32 v59, 0xbfb8aa3b, v59
	v_mul_f32_e32 v60, 0xbfb8aa3b, v60
	v_mul_f32_e32 v61, 0xbfb8aa3b, v61
	v_exp_f32_e32 v62, v62
	v_exp_f32_e32 v63, v63
	v_exp_f32_e32 v64, v64
	v_exp_f32_e32 v65, v65
	v_exp_f32_e32 v58, v58
	v_exp_f32_e32 v59, v59
	v_exp_f32_e32 v60, v60
	v_exp_f32_e32 v61, v61
	v_add_f32_e32 v62, 1.0, v62
	v_add_f32_e32 v63, 1.0, v63
	v_add_f32_e32 v64, 1.0, v64
	v_add_f32_e32 v65, 1.0, v65
	v_add_f32_e32 v58, 1.0, v58
	v_add_f32_e32 v59, 1.0, v59
	v_add_f32_e32 v60, 1.0, v60
	v_add_f32_e32 v61, 1.0, v61
	v_rcp_f32_e32 v62, v62
	v_rcp_f32_e32 v63, v63
	v_rcp_f32_e32 v64, v64
	v_rcp_f32_e32 v65, v65
	v_rcp_f32_e32 v58, v58
	v_rcp_f32_e32 v59, v59
	v_rcp_f32_e32 v60, v60
	v_rcp_f32_e32 v61, v61
	v_lshlrev_b32_e32 v234, 16, v198
	v_and_b32_e32 v235, 0xffff0000, v198
	v_lshlrev_b32_e32 v236, 16, v199
	v_and_b32_e32 v237, 0xffff0000, v199
	v_pk_mul_f32 v[62:63], v[62:63], v[234:235]
	v_pk_mul_f32 v[64:65], v[64:65], v[236:237]
	v_lshlrev_b32_e32 v234, 16, v200
	v_and_b32_e32 v235, 0xffff0000, v200
	v_lshlrev_b32_e32 v236, 16, v201
	v_and_b32_e32 v237, 0xffff0000, v201
	v_pk_mul_f32 v[58:59], v[58:59], v[234:235]
	v_pk_mul_f32 v[60:61], v[60:61], v[236:237]
	s_nop 0
	v_cvt_pk_bf16_f32 v198, v62, v63
	v_cvt_pk_bf16_f32 v199, v64, v65
	v_cvt_pk_bf16_f32 v200, v58, v59
	v_cvt_pk_bf16_f32 v201, v60, v61
	s_mov_b64 vcc, 0x8000
	v_lshl_add_u64 v[242:243], v[244:245], 0, vcc
	global_store_dwordx4 v[242:243], v[198:201], off offset:256
	v_pk_add_f32 v[54:55], v[54:55], v[226:227]
	v_pk_add_f32 v[56:57], v[56:57], v[228:229]
	v_pk_add_f32 v[50:51], v[50:51], v[230:231]
	v_pk_add_f32 v[52:53], v[52:53], v[232:233]
	v_mul_f32_e32 v54, 0xbfb8aa3b, v54
	v_mul_f32_e32 v55, 0xbfb8aa3b, v55
	v_mul_f32_e32 v56, 0xbfb8aa3b, v56
	v_mul_f32_e32 v57, 0xbfb8aa3b, v57
	v_mul_f32_e32 v50, 0xbfb8aa3b, v50
	v_mul_f32_e32 v51, 0xbfb8aa3b, v51
	v_mul_f32_e32 v52, 0xbfb8aa3b, v52
	v_mul_f32_e32 v53, 0xbfb8aa3b, v53
	v_exp_f32_e32 v54, v54
	v_exp_f32_e32 v55, v55
	v_exp_f32_e32 v56, v56
	v_exp_f32_e32 v57, v57
	v_exp_f32_e32 v50, v50
	v_exp_f32_e32 v51, v51
	v_exp_f32_e32 v52, v52
	v_exp_f32_e32 v53, v53
	v_add_f32_e32 v54, 1.0, v54
	v_add_f32_e32 v55, 1.0, v55
	v_add_f32_e32 v56, 1.0, v56
	v_add_f32_e32 v57, 1.0, v57
	v_add_f32_e32 v50, 1.0, v50
	v_add_f32_e32 v51, 1.0, v51
	v_add_f32_e32 v52, 1.0, v52
	v_add_f32_e32 v53, 1.0, v53
	v_rcp_f32_e32 v54, v54
	v_rcp_f32_e32 v55, v55
	v_rcp_f32_e32 v56, v56
	v_rcp_f32_e32 v57, v57
	v_rcp_f32_e32 v50, v50
	v_rcp_f32_e32 v51, v51
	v_rcp_f32_e32 v52, v52
	v_rcp_f32_e32 v53, v53
	v_lshlrev_b32_e32 v234, 16, v202
	v_and_b32_e32 v235, 0xffff0000, v202
	v_lshlrev_b32_e32 v236, 16, v203
	v_and_b32_e32 v237, 0xffff0000, v203
	v_pk_mul_f32 v[54:55], v[54:55], v[234:235]
	v_pk_mul_f32 v[56:57], v[56:57], v[236:237]
	v_lshlrev_b32_e32 v234, 16, v204
	v_and_b32_e32 v235, 0xffff0000, v204
	v_lshlrev_b32_e32 v236, 16, v205
	v_and_b32_e32 v237, 0xffff0000, v205
	v_pk_mul_f32 v[50:51], v[50:51], v[234:235]
	v_pk_mul_f32 v[52:53], v[52:53], v[236:237]
	s_nop 0
	v_cvt_pk_bf16_f32 v202, v54, v55
	v_cvt_pk_bf16_f32 v203, v56, v57
	v_cvt_pk_bf16_f32 v204, v50, v51
	v_cvt_pk_bf16_f32 v205, v52, v53
	s_mov_b64 vcc, 0x10000
	v_lshl_add_u64 v[250:251], v[244:245], 0, vcc
	global_store_dwordx4 v[250:251], v[202:205], off offset:256
	v_pk_add_f32 v[38:39], v[38:39], v[226:227]
	v_pk_add_f32 v[40:41], v[40:41], v[228:229]
	v_pk_add_f32 v[34:35], v[34:35], v[230:231]
	v_pk_add_f32 v[36:37], v[36:37], v[232:233]
	v_mul_f32_e32 v38, 0xbfb8aa3b, v38
; __device__ __forceinline__ unsigned cvt_pk_bf16(float lo, float hi) { const f32x2 v = {lo, hi}; const bf16x2_t b = __builtin_convertvector(v, bf16x2_t); return __builtin_bit_cast(unsigned, b); }
; __device__ __forceinline__ float bflo(unsigned u) { return __uint_as_float(u << 16); }
; __device__ __forceinline__ float bfhi(unsigned u) { return __uint_as_float(u & 0xffff0000u); }
; __device__ __forceinline__ float sigmoidf_(float x) { return __builtin_amdgcn_rcpf(1.0f + __expf(-x)); }
;     __device__ __forceinline__ void operator()(const AccT& acc, const Unit& u, int wr, int wc, int fr, int fq) const {
;     ...
;         for (int bj = 0; bj < 2; ++bj) {
;             const int col = u.pn * 256 + bj * 128 + wc * 32 + 8 * fq;
;             const f32x4 b0 = *(const f32x4*)(bias + col), b1 = *(const f32x4*)(bias + col + 4);
; #pragma unroll
;             for (int ai = 0; ai < 2; ++ai)
; #pragma unroll
;                 for (int m = 0; m < 4; ++m) {
;                     const int row = u.pm * 256 + ai * 128 + wr * 64 + m * 16 + fr;
;                     const u32x4 y = *(const u32x4*)(Y + (size_t)row * 1024 + col);
;                     const f32x4 v0 = acc[ai][bj][m][0] + b0, v1 = acc[ai][bj][m][1] + b1;
;                     u32x4 w;
;                     w.x = cvt_pk_bf16(bflo(y.x) * sigmoidf_(v0[0]), bfhi(y.x) * sigmoidf_(v0[1]));
;                     w.y = cvt_pk_bf16(bflo(y.y) * sigmoidf_(v0[2]), bfhi(y.y) * sigmoidf_(v0[3]));
;                     w.z = cvt_pk_bf16(bflo(y.z) * sigmoidf_(v1[0]), bfhi(y.z) * sigmoidf_(v1[1]));
;                     w.w = cvt_pk_bf16(bflo(y.w) * sigmoidf_(v1[2]), bfhi(y.w) * sigmoidf_(v1[3]));
;                     *(u32x4*)(O + (size_t)row * 1024 + col) = w;
	v_mul_f32_e32 v39, 0xbfb8aa3b, v39
	v_mul_f32_e32 v40, 0xbfb8aa3b, v40
	v_mul_f32_e32 v41, 0xbfb8aa3b, v41
	v_mul_f32_e32 v34, 0xbfb8aa3b, v34
	v_mul_f32_e32 v35, 0xbfb8aa3b, v35
	v_mul_f32_e32 v36, 0xbfb8aa3b, v36
	v_mul_f32_e32 v37, 0xbfb8aa3b, v37
	v_exp_f32_e32 v38, v38
	v_exp_f32_e32 v39, v39
	v_exp_f32_e32 v40, v40
	v_exp_f32_e32 v41, v41
	v_exp_f32_e32 v34, v34
	v_exp_f32_e32 v35, v35
	v_exp_f32_e32 v36, v36
	v_exp_f32_e32 v37, v37
	v_add_f32_e32 v38, 1.0, v38
	v_add_f32_e32 v39, 1.0, v39
	v_add_f32_e32 v40, 1.0, v40
	v_add_f32_e32 v41, 1.0, v41
	v_add_f32_e32 v34, 1.0, v34
	v_add_f32_e32 v35, 1.0, v35
	v_add_f32_e32 v36, 1.0, v36
	v_add_f32_e32 v37, 1.0, v37
	v_rcp_f32_e32 v38, v38
	v_rcp_f32_e32 v39, v39
	v_rcp_f32_e32 v40, v40
	v_rcp_f32_e32 v41, v41
	v_rcp_f32_e32 v34, v34
	v_rcp_f32_e32 v35, v35
	v_rcp_f32_e32 v36, v36
	v_rcp_f32_e32 v37, v37
	v_lshlrev_b32_e32 v234, 16, v206
	v_and_b32_e32 v235, 0xffff0000, v206
	v_lshlrev_b32_e32 v236, 16, v207
	v_and_b32_e32 v237, 0xffff0000, v207
	v_pk_mul_f32 v[38:39], v[38:39], v[234:235]
	v_pk_mul_f32 v[40:41], v[40:41], v[236:237]
	v_lshlrev_b32_e32 v234, 16, v208
	v_and_b32_e32 v235, 0xffff0000, v208
	v_lshlrev_b32_e32 v236, 16, v209
	v_and_b32_e32 v237, 0xffff0000, v209
	v_pk_mul_f32 v[34:35], v[34:35], v[234:235]
	v_pk_mul_f32 v[36:37], v[36:37], v[236:237]
	s_nop 0
	v_cvt_pk_bf16_f32 v206, v38, v39
	v_cvt_pk_bf16_f32 v207, v40, v41
	v_cvt_pk_bf16_f32 v208, v34, v35
	v_cvt_pk_bf16_f32 v209, v36, v37
	s_mov_b64 vcc, 0x18000
	v_lshl_add_u64 v[242:243], v[244:245], 0, vcc
	global_store_dwordx4 v[242:243], v[206:209], off offset:256
	v_pk_add_f32 v[30:31], v[30:31], v[226:227]
	v_pk_add_f32 v[32:33], v[32:33], v[228:229]
	v_pk_add_f32 v[26:27], v[26:27], v[230:231]
	v_pk_add_f32 v[28:29], v[28:29], v[232:233]
	v_mul_f32_e32 v30, 0xbfb8aa3b, v30
	v_mul_f32_e32 v31, 0xbfb8aa3b, v31
	v_mul_f32_e32 v32, 0xbfb8aa3b, v32
	v_mul_f32_e32 v33, 0xbfb8aa3b, v33
	v_mul_f32_e32 v26, 0xbfb8aa3b, v26
	v_mul_f32_e32 v27, 0xbfb8aa3b, v27
	v_mul_f32_e32 v28, 0xbfb8aa3b, v28
	v_mul_f32_e32 v29, 0xbfb8aa3b, v29
	v_exp_f32_e32 v30, v30
	v_exp_f32_e32 v31, v31
	v_exp_f32_e32 v32, v32
	v_exp_f32_e32 v33, v33
	v_exp_f32_e32 v26, v26
	v_exp_f32_e32 v27, v27
	v_exp_f32_e32 v28, v28
	v_exp_f32_e32 v29, v29
	v_add_f32_e32 v30, 1.0, v30
	v_add_f32_e32 v31, 1.0, v31
	v_add_f32_e32 v32, 1.0, v32
	v_add_f32_e32 v33, 1.0, v33
	v_add_f32_e32 v26, 1.0, v26
	v_add_f32_e32 v27, 1.0, v27
	v_add_f32_e32 v28, 1.0, v28
	v_add_f32_e32 v29, 1.0, v29
	v_rcp_f32_e32 v30, v30
	v_rcp_f32_e32 v31, v31
	v_rcp_f32_e32 v32, v32
	v_rcp_f32_e32 v33, v33
	v_rcp_f32_e32 v26, v26
	v_rcp_f32_e32 v27, v27
	v_rcp_f32_e32 v28, v28
	v_rcp_f32_e32 v29, v29
	v_lshlrev_b32_e32 v234, 16, v210
	v_and_b32_e32 v235, 0xffff0000, v210
	v_lshlrev_b32_e32 v236, 16, v211
	v_and_b32_e32 v237, 0xffff0000, v211
	v_pk_mul_f32 v[30:31], v[30:31], v[234:235]
	v_pk_mul_f32 v[32:33], v[32:33], v[236:237]
	v_lshlrev_b32_e32 v234, 16, v212
	v_and_b32_e32 v235, 0xffff0000, v212
	v_lshlrev_b32_e32 v236, 16, v213
	v_and_b32_e32 v237, 0xffff0000, v213
	v_pk_mul_f32 v[26:27], v[26:27], v[234:235]
	v_pk_mul_f32 v[28:29], v[28:29], v[236:237]
	s_nop 0
	v_cvt_pk_bf16_f32 v210, v30, v31
	v_cvt_pk_bf16_f32 v211, v32, v33
	v_cvt_pk_bf16_f32 v212, v26, v27
	v_cvt_pk_bf16_f32 v213, v28, v29
	s_mov_b64 vcc, 0x40000
	v_lshl_add_u64 v[250:251], v[244:245], 0, vcc
	global_store_dwordx4 v[250:251], v[210:213], off offset:256
	v_pk_add_f32 v[22:23], v[22:23], v[226:227]
	v_pk_add_f32 v[24:25], v[24:25], v[228:229]
	v_pk_add_f32 v[18:19], v[18:19], v[230:231]
	v_pk_add_f32 v[20:21], v[20:21], v[232:233]
	v_mul_f32_e32 v22, 0xbfb8aa3b, v22
	v_mul_f32_e32 v23, 0xbfb8aa3b, v23
	v_mul_f32_e32 v24, 0xbfb8aa3b, v24
	v_mul_f32_e32 v25, 0xbfb8aa3b, v25
	v_mul_f32_e32 v18, 0xbfb8aa3b, v18
	v_mul_f32_e32 v19, 0xbfb8aa3b, v19
	v_mul_f32_e32 v20, 0xbfb8aa3b, v20
	v_mul_f32_e32 v21, 0xbfb8aa3b, v21
	v_exp_f32_e32 v22, v22
	v_exp_f32_e32 v23, v23
	v_exp_f32_e32 v24, v24
	v_exp_f32_e32 v25, v25
	v_exp_f32_e32 v18, v18
	v_exp_f32_e32 v19, v19
	v_exp_f32_e32 v20, v20
	v_exp_f32_e32 v21, v21
	v_add_f32_e32 v22, 1.0, v22
	v_add_f32_e32 v23, 1.0, v23
	v_add_f32_e32 v24, 1.0, v24
	v_add_f32_e32 v25, 1.0, v25
	v_add_f32_e32 v18, 1.0, v18
	v_add_f32_e32 v19, 1.0, v19
	v_add_f32_e32 v20, 1.0, v20
	v_add_f32_e32 v21, 1.0, v21
	v_rcp_f32_e32 v22, v22
	v_rcp_f32_e32 v23, v23
	v_rcp_f32_e32 v24, v24
	v_rcp_f32_e32 v25, v25
	v_rcp_f32_e32 v18, v18
	v_rcp_f32_e32 v19, v19
	v_rcp_f32_e32 v20, v20
; __device__ __forceinline__ unsigned cvt_pk_bf16(float lo, float hi) { const f32x2 v = {lo, hi}; const bf16x2_t b = __builtin_convertvector(v, bf16x2_t); return __builtin_bit_cast(unsigned, b); }
; __device__ __forceinline__ float bflo(unsigned u) { return __uint_as_float(u << 16); }
; __device__ __forceinline__ float bfhi(unsigned u) { return __uint_as_float(u & 0xffff0000u); }
; __device__ __forceinline__ float sigmoidf_(float x) { return __builtin_amdgcn_rcpf(1.0f + __expf(-x)); }
; template <class Epi>
; __device__ __forceinline__ void gemm_phase(LAS unsigned char* lds, const Gemm g, const TileOrder& S, const Epi& E) {
;     ...
;         if (!has_next) break;
;     __device__ __forceinline__ void operator()(const AccT& acc, const Unit& u, int wr, int wc, int fr, int fq) const {
;     ...
;         for (int bj = 0; bj < 2; ++bj) {
;             const int col = u.pn * 256 + bj * 128 + wc * 32 + 8 * fq;
;             const f32x4 b0 = *(const f32x4*)(bias + col), b1 = *(const f32x4*)(bias + col + 4);
; #pragma unroll
;             for (int ai = 0; ai < 2; ++ai)
; #pragma unroll
;                 for (int m = 0; m < 4; ++m) {
;                     const int row = u.pm * 256 + ai * 128 + wr * 64 + m * 16 + fr;
;                     const u32x4 y = *(const u32x4*)(Y + (size_t)row * 1024 + col);
;                     const f32x4 v0 = acc[ai][bj][m][0] + b0, v1 = acc[ai][bj][m][1] + b1;
;                     u32x4 w;
;                     w.x = cvt_pk_bf16(bflo(y.x) * sigmoidf_(v0[0]), bfhi(y.x) * sigmoidf_(v0[1]));
;                     w.y = cvt_pk_bf16(bflo(y.y) * sigmoidf_(v0[2]), bfhi(y.y) * sigmoidf_(v0[3]));
;                     w.z = cvt_pk_bf16(bflo(y.z) * sigmoidf_(v1[0]), bfhi(y.z) * sigmoidf_(v1[1]));
;                     w.w = cvt_pk_bf16(bflo(y.w) * sigmoidf_(v1[2]), bfhi(y.w) * sigmoidf_(v1[3]));
;                     *(u32x4*)(O + (size_t)row * 1024 + col) = w;
;                 }
	v_rcp_f32_e32 v21, v21
	v_lshlrev_b32_e32 v234, 16, v214
	v_and_b32_e32 v235, 0xffff0000, v214
	v_lshlrev_b32_e32 v236, 16, v215
	v_and_b32_e32 v237, 0xffff0000, v215
	v_pk_mul_f32 v[22:23], v[22:23], v[234:235]
	v_pk_mul_f32 v[24:25], v[24:25], v[236:237]
	v_lshlrev_b32_e32 v234, 16, v216
	v_and_b32_e32 v235, 0xffff0000, v216
	v_lshlrev_b32_e32 v236, 16, v217
	v_and_b32_e32 v237, 0xffff0000, v217
	v_pk_mul_f32 v[18:19], v[18:19], v[234:235]
	v_pk_mul_f32 v[20:21], v[20:21], v[236:237]
	s_nop 0
	v_cvt_pk_bf16_f32 v214, v22, v23
	v_cvt_pk_bf16_f32 v215, v24, v25
	v_cvt_pk_bf16_f32 v216, v18, v19
	v_cvt_pk_bf16_f32 v217, v20, v21
	s_mov_b64 vcc, 0x48000
	v_lshl_add_u64 v[242:243], v[244:245], 0, vcc
	global_store_dwordx4 v[242:243], v[214:217], off offset:256
	v_pk_add_f32 v[14:15], v[14:15], v[226:227]
	v_pk_add_f32 v[16:17], v[16:17], v[228:229]
	v_pk_add_f32 v[10:11], v[10:11], v[230:231]
	v_pk_add_f32 v[12:13], v[12:13], v[232:233]
	v_mul_f32_e32 v14, 0xbfb8aa3b, v14
	v_mul_f32_e32 v15, 0xbfb8aa3b, v15
	v_mul_f32_e32 v16, 0xbfb8aa3b, v16
	v_mul_f32_e32 v17, 0xbfb8aa3b, v17
	v_mul_f32_e32 v10, 0xbfb8aa3b, v10
	v_mul_f32_e32 v11, 0xbfb8aa3b, v11
	v_mul_f32_e32 v12, 0xbfb8aa3b, v12
	v_mul_f32_e32 v13, 0xbfb8aa3b, v13
	v_exp_f32_e32 v14, v14
	v_exp_f32_e32 v15, v15
	v_exp_f32_e32 v16, v16
	v_exp_f32_e32 v17, v17
	v_exp_f32_e32 v10, v10
	v_exp_f32_e32 v11, v11
	v_exp_f32_e32 v12, v12
	v_exp_f32_e32 v13, v13
	v_add_f32_e32 v14, 1.0, v14
	v_add_f32_e32 v15, 1.0, v15
	v_add_f32_e32 v16, 1.0, v16
	v_add_f32_e32 v17, 1.0, v17
	v_add_f32_e32 v10, 1.0, v10
	v_add_f32_e32 v11, 1.0, v11
	v_add_f32_e32 v12, 1.0, v12
	v_add_f32_e32 v13, 1.0, v13
	v_rcp_f32_e32 v14, v14
	v_rcp_f32_e32 v15, v15
	v_rcp_f32_e32 v16, v16
	v_rcp_f32_e32 v17, v17
	v_rcp_f32_e32 v10, v10
	v_rcp_f32_e32 v11, v11
	v_rcp_f32_e32 v12, v12
	v_rcp_f32_e32 v13, v13
	v_lshlrev_b32_e32 v234, 16, v218
	v_and_b32_e32 v235, 0xffff0000, v218
	v_lshlrev_b32_e32 v236, 16, v219
	v_and_b32_e32 v237, 0xffff0000, v219
	v_pk_mul_f32 v[14:15], v[14:15], v[234:235]
	v_pk_mul_f32 v[16:17], v[16:17], v[236:237]
	v_lshlrev_b32_e32 v234, 16, v220
	v_and_b32_e32 v235, 0xffff0000, v220
	v_lshlrev_b32_e32 v236, 16, v221
	v_and_b32_e32 v237, 0xffff0000, v221
	v_pk_mul_f32 v[10:11], v[10:11], v[234:235]
	v_pk_mul_f32 v[12:13], v[12:13], v[236:237]
	s_nop 0
	v_cvt_pk_bf16_f32 v218, v14, v15
	v_cvt_pk_bf16_f32 v219, v16, v17
	v_cvt_pk_bf16_f32 v220, v10, v11
	v_cvt_pk_bf16_f32 v221, v12, v13
	s_mov_b64 vcc, 0x50000
	v_lshl_add_u64 v[250:251], v[244:245], 0, vcc
	global_store_dwordx4 v[250:251], v[218:221], off offset:256
	v_pk_add_f32 v[6:7], v[6:7], v[226:227]
	v_pk_add_f32 v[8:9], v[8:9], v[228:229]
	v_pk_add_f32 v[2:3], v[2:3], v[230:231]
	v_pk_add_f32 v[4:5], v[4:5], v[232:233]
	v_mul_f32_e32 v6, 0xbfb8aa3b, v6
	v_mul_f32_e32 v7, 0xbfb8aa3b, v7
	v_mul_f32_e32 v8, 0xbfb8aa3b, v8
	v_mul_f32_e32 v9, 0xbfb8aa3b, v9
	v_mul_f32_e32 v2, 0xbfb8aa3b, v2
	v_mul_f32_e32 v3, 0xbfb8aa3b, v3
	v_mul_f32_e32 v4, 0xbfb8aa3b, v4
	v_mul_f32_e32 v5, 0xbfb8aa3b, v5
	v_exp_f32_e32 v6, v6
	v_exp_f32_e32 v7, v7
	v_exp_f32_e32 v8, v8
	v_exp_f32_e32 v9, v9
	v_exp_f32_e32 v2, v2
	v_exp_f32_e32 v3, v3
	v_exp_f32_e32 v4, v4
	v_exp_f32_e32 v5, v5
	v_add_f32_e32 v6, 1.0, v6
	v_add_f32_e32 v7, 1.0, v7
	v_add_f32_e32 v8, 1.0, v8
	v_add_f32_e32 v9, 1.0, v9
	v_add_f32_e32 v2, 1.0, v2
	v_add_f32_e32 v3, 1.0, v3
	v_add_f32_e32 v4, 1.0, v4
	v_add_f32_e32 v5, 1.0, v5
	v_rcp_f32_e32 v6, v6
	v_rcp_f32_e32 v7, v7
	v_rcp_f32_e32 v8, v8
	v_rcp_f32_e32 v9, v9
	v_rcp_f32_e32 v2, v2
	v_rcp_f32_e32 v3, v3
	v_rcp_f32_e32 v4, v4
	v_rcp_f32_e32 v5, v5
	v_lshlrev_b32_e32 v234, 16, v222
	v_and_b32_e32 v235, 0xffff0000, v222
	v_lshlrev_b32_e32 v236, 16, v223
	v_and_b32_e32 v237, 0xffff0000, v223
	v_pk_mul_f32 v[6:7], v[6:7], v[234:235]
	v_pk_mul_f32 v[8:9], v[8:9], v[236:237]
	v_lshlrev_b32_e32 v234, 16, v224
	v_and_b32_e32 v235, 0xffff0000, v224
	v_lshlrev_b32_e32 v236, 16, v225
	v_and_b32_e32 v237, 0xffff0000, v225
	v_pk_mul_f32 v[2:3], v[2:3], v[234:235]
	v_pk_mul_f32 v[4:5], v[4:5], v[236:237]
	s_nop 0
	v_cvt_pk_bf16_f32 v222, v6, v7
	v_cvt_pk_bf16_f32 v223, v8, v9
	v_cvt_pk_bf16_f32 v224, v2, v3
	v_cvt_pk_bf16_f32 v225, v4, v5
	s_mov_b64 vcc, 0x58000
	v_lshl_add_u64 v[242:243], v[244:245], 0, vcc
	global_store_dwordx4 v[242:243], v[222:225], off offset:256
	s_and_b64 vcc, exec, s[4:5]
	s_cbranch_vccz .LBB0_752
	s_waitcnt vmcnt(0)
	s_cmpk_gt_u32 s25, 0xff
	v_readlane_b32 s91, v252, 25
	s_cbranch_scc1 .LBB0_763
	s_barrier
